# half of WGs run combine before attention (ph5) and conv-mixer after SSD scan (ph4)
# baseline (speedup 1.0000x reference)
; __global__ void __launch_bounds__(NTHR, 2) mk_fwd(Args a_by_value) {
;     ...
;         } else if (PH_EN(5) && k == 5) {
;             const int vcu = (G % 8 == 0) ? (bid % 8) * (G / 8) + bid / 8 : bid;
;             for (int rep = 0; rep < REP_ATT; ++rep) for (int unit = vcu; unit < 512; unit += G) attn_unit(a, layer, (unit & 255) * 2 + (unit >> 8), lds);
;             for (int rep5 = 0; rep5 < REP_CMB; ++rep5) ssd_combine_rows(a, G);
.LBB0_60:
	s_cmp_gt_i32 s9, 4
	s_mov_b64 s[2:3], -1
	s_cbranch_scc0 .LBB0_91
	s_bfe_u32 s2, s36, 0x10003
	s_nop 1
	v_writelane_b32 v255, s2, 42
	s_cmp_eq_u32 s2, 1
	s_cbranch_scc1 .LBB0_83
.Lp5_attn_entry:
	v_readlane_b32 s2, v253, 14
	v_readlane_b32 s3, v253, 15
	s_andn2_b64 vcc, exec, s[2:3]
	s_mov_b32 s10, s36
	s_cbranch_vccz .LBB0_63
	s_cmpk_gt_i32 s10, 0x1ff
	s_cbranch_scc0 .LBB0_64
	s_branch .LBB0_83

; __device__ __forceinline__ int ltid() { int t = threadIdx.x; asm volatile("" : "+v"(t)); return t; }
; __device__ __forceinline__ int lbid() { int t = blockIdx.x; asm volatile("" : "+s"(t)); return t; }
; #define wt16(p, v) wt16b(WSB, (p), (v))
; __device__ __forceinline__ u32x4 pack8(const float (&f)[8]) { u32x4 v; v.x = cvt_pk_bf16(f[0], f[1]); v.y = cvt_pk_bf16(f[2], f[3]); v.z = cvt_pk_bf16(f[4], f[5]); v.w = cvt_pk_bf16(f[6], f[7]); return v; }
; __device__ __forceinline__ float silu_f(float x) { return x * __builtin_amdgcn_rcpf(1.f + __expf(-x)); }
; __device__ __forceinline__ void ssd_combine_rows(CArgs a, int G) {
;     const int lane = ltid() & 63, wave = ltid() >> 6;
;     const int gw = lbid() * NWAVES + wave, NGW = G * NWAVES;
;     const unsigned char* WSB = a->ws;
;     const bf16_t* U = (const bf16_t*)(a->ws + WS_U); bf16_t* Y = (bf16_t*)(a->ws + WS_Y);
;     const bf16_t* yb = (const bf16_t*)(a->ws + WS_YF);
;     const int c0 = lane * 16;
;     auto load = [&](int row, u32x4 (&raw)[6]) {
; #pragma unroll
;         for (int hf = 0; hf < 2; ++hf) { raw[3 * hf] = *(const u32x4*)(Y + (size_t)row * 2048 + c0 + 8 * hf); raw[3 * hf + 1] = *(const u32x4*)(yb + (size_t)row * 1024 + c0 + 8 * hf);
;             raw[3 * hf + 2] = *(const u32x4*)(U + (size_t)row * NU + UZ + c0 + 8 * hf); }
;     };
;     auto finish = [&](int row, const u32x4 (&raw)[6]) {
;         float g[16]; float ss = 0.f;
; #pragma unroll
;         for (int hf = 0; hf < 2; ++hf) {
;             float f[8], bb[8], z[8];
;             unpack8(raw[3 * hf], f); unpack8(raw[3 * hf + 1], bb); unpack8(raw[3 * hf + 2], z);
; #pragma unroll
;             for (int e = 0; e < 8; ++e) { const float y = (f[e] + bb[e]) * silu_f(z[e]); g[8 * hf + e] = y; ss += y * y; }
;         }
;         ss += __shfl_xor(ss, 1); ss += __shfl_xor(ss, 2); ss += __shfl_xor(ss, 4); ss += __shfl_xor(ss, 8); ss += __shfl_xor(ss, 16);
;         const float r = rsqrtf(ss * (1.f / 512.f) + EPS);
;         float o0[8], o1[8];
; #pragma unroll
;         for (int e = 0; e < 8; ++e) { o0[e] = g[e] * r; o1[e] = g[8 + e] * r; }
;         wt16(Y + (size_t)row * 2048 + c0, pack8(o0)); wt16(Y + (size_t)row * 2048 + c0 + 8, pack8(o1));
;     };
.LBB0_83:
	v_readlane_b32 s2, v255, 42
	s_nop 3
	s_cmp_eq_u32 s2, 2
	s_cbranch_scc1 .Lp5_done
	v_mov_b32_e32 v0, v244
	v_mov_b32_e32 v2, v244
	v_readlane_b32 s2, v253, 0
	v_ashrrev_i32_e32 v2, 6, v2
	s_nop 0
	v_lshl_add_u32 v56, s2, 3, v2
	v_cmp_gt_i32_e32 vcc, s65, v56
	s_waitcnt lgkmcnt(0)
	s_and_saveexec_b64 s[16:17], vcc
	v_readlane_b32 s12, v255, 4
	v_readlane_b32 s13, v255, 5
	s_cbranch_execz .LBB0_90
	s_load_dwordx2 s[60:61], s[6:7], 0xe8
	v_lshlrev_b32_e32 v0, 5, v0
	v_and_b32_e32 v0, 0x7e0, v0
	s_mov_b64 s[10:11], 0x10a00000
	v_xor_b32_e32 v3, 1, v247
	s_waitcnt lgkmcnt(0)
	v_lshl_add_u64 v[4:5], s[60:61], 0, v[0:1]
	v_lshl_add_u64 v[50:51], v[4:5], 0, s[10:11]
	s_mov_b64 s[10:11], 0x18a00000
	v_lshl_add_u64 v[52:53], v[4:5], 0, s[10:11]
	s_mov_b64 s[10:11], 0x3a00000
	v_lshl_add_u64 v[54:55], v[4:5], 0, s[10:11]
	v_and_b32_e32 v4, 64, v247
	v_add_u32_e32 v4, 64, v4
	v_cmp_lt_i32_e32 vcc, v3, v4
	v_lshlrev_b32_e32 v2, 12, v2
	v_lshl_add_u32 v71, s2, 15, v2
	v_cndmask_b32_e32 v3, v247, v3, vcc
	s_waitcnt vmcnt(16)
	v_lshlrev_b32_e32 v66, 2, v3
	v_xor_b32_e32 v3, 2, v247
	v_cmp_lt_i32_e32 vcc, v3, v4
	v_readlane_b32 s2, v254, 56
	s_and_b32 s61, s61, 0xffff
	v_cndmask_b32_e32 v3, v247, v3, vcc
	v_lshlrev_b32_e32 v67, 2, v3
	v_xor_b32_e32 v3, 4, v247
	v_cmp_lt_i32_e32 vcc, v3, v4
	v_add_u32_e32 v72, s2, v0
	s_mov_b64 s[18:19], 0
	v_cndmask_b32_e32 v3, v247, v3, vcc
	v_lshlrev_b32_e32 v68, 2, v3
	v_xor_b32_e32 v3, 8, v247
	v_cmp_lt_i32_e32 vcc, v3, v4
	s_nop 1
	v_cndmask_b32_e32 v3, v247, v3, vcc
	v_lshlrev_b32_e32 v69, 2, v3
	v_xor_b32_e32 v3, 16, v247
	v_cmp_lt_i32_e32 vcc, v3, v4
	s_nop 1
	v_cndmask_b32_e32 v3, v247, v3, vcc
	v_lshlrev_b32_e32 v70, 2, v3
	s_branch .LBB0_86

; __device__ __forceinline__ void ssd_combine_rows(CArgs a, int G) {
;     ...
;     for (int row = gw; row < T; row += 2 * NGW) {
;         const int row2 = row + NGW;
;         u32x4 ra[6], rb[6];
;         load(row, ra);
;         if (row2 < T) load(row2, rb);
;         finish(row, ra);
;         if (row2 < T) finish(row2, rb);
;     }
; __global__ void __launch_bounds__(NTHR, 2) mk_fwd(Args a_by_value) {
;     ...
;         } else if (PH_EN(5) && k == 5) {
;             const int vcu = (G % 8 == 0) ? (bid % 8) * (G / 8) + bid / 8 : bid;
;             for (int rep = 0; rep < REP_ATT; ++rep) for (int unit = vcu; unit < 512; unit += G) attn_unit(a, layer, (unit & 255) * 2 + (unit >> 8), lds);
;             for (int rep5 = 0; rep5 < REP_CMB; ++rep5) ssd_combine_rows(a, G);
.LBB0_90:
	s_or_b64 exec, exec, s[16:17]
	v_readlane_b32 s2, v255, 42
	s_nop 3
	s_cmp_eq_u32 s2, 1
	s_cbranch_scc0 .Lp5_done
	s_mov_b32 s2, 2
	s_nop 1
	v_writelane_b32 v255, s2, 42
	s_branch .Lp5_attn_entry

; __global__ void __launch_bounds__(NTHR, 2) mk_fwd(Args a_by_value) {
;     ...
;         } else if (PH_EN(4) && k == 4) {
;             unsigned* subc = (unsigned*)(ws + WS_BAR) + XCD_BAR_WORDS + 64 * (layer * 8);
;             for (int item = bid; item < 256; item += G) { ssd_bc_slice(a, layer, item); sub_arrive(subc + 64 * (item >> 5)); }
.LBB0_91:
	s_and_b64 vcc, exec, s[2:3]
	s_cbranch_vccz .LBB0_209
	s_bfe_u32 s2, s36, 0x10003
	s_nop 1
	v_writelane_b32 v255, s2, 41
	s_lshl_b32 s2, s8, 9
	s_ashr_i32 s3, s2, 31
	s_lshl_b64 s[2:3], s[2:3], 2
	v_readlane_b32 s10, v253, 18
	s_add_u32 s2, s10, s2
	v_writelane_b32 v255, s2, 18
	v_readlane_b32 s2, v253, 19
	s_addc_u32 s11, s2, s3
	s_cmpk_lt_i32 s36, 0x100
	s_cselect_b64 s[28:29], -1, 0
	s_mov_b64 s[2:3], -1
	s_and_b64 vcc, exec, s[28:29]
	s_mul_hi_i32 s37, s8, 0x1800
	s_mul_i32 s88, s8, 0x1800
	s_cbranch_vccnz .LBB0_94
	s_ashr_i32 s2, s8, 31
	v_writelane_b32 v255, s2, 12
	s_mov_b64 s[2:3], 0

; __global__ void __launch_bounds__(NTHR, 2) mk_fwd(Args a_by_value) {
;     ...
;             for (int rep4 = 0; rep4 < REP_P4R; ++rep4) {
;             if (P4_EN(1)) {
;                 pg8::Gemm g{U + UQ, (const bf16_t*)(wsw + W_UQ), T, 768, 256, NU, 256}; pg8::StaticOrder S; S.init(T, 768, G, bid);
;                 EpiQ E{ws, (bf16_t*)(ws + WS_QR), (const float*)(ws + WS_CTL + CTL_QSS)};
;                 pg8::gemm_phase<EpiQ, pg8::StaticOrder, false>(lds, g, S, E);
;             }
;             if (P4_EN(2)) {
;                 pg8::Gemm g{U + UKV, (const bf16_t*)(wsw + W_UKV), T, 1024, 128, NU, 128}; pg8::StaticOrder S; S.init(T, 1024, G, bid);
;                 EpiKV E{ws, U, (const float*)(ws + WS_CTL + CTL_KVSS), a->mla_khn + layer * 96, (const float2*)(ws + WS_CS), (bf16_t*)(ws + WS_KF), (bf16_t*)(ws + WS_VT)};
;                 pg8::gemm_phase<EpiKV, pg8::StaticOrder, false>(lds, g, S, E);
;             }
;             if (P4_EN(3)) conv_mixer_rows(a, layer, G);
;             }
;             for (int item = bid; item < 256; item += G) { sub_wait(subc + 64 * (item >> 5), 32u); ssd_item(a, layer, item, lds); }
.LBB0_168:
	v_readlane_b32 s2, v255, 41
	s_nop 3
	s_cmp_eq_u32 s2, 1
	s_cbranch_scc1 .Lp4_ssd_entry

; __global__ void __launch_bounds__(NTHR, 2) mk_fwd(Args a_by_value) {
;     ...
;             if (P4_EN(3)) conv_mixer_rows(a, layer, G);
;             }
;             for (int item = bid; item < 256; item += G) { sub_wait(subc + 64 * (item >> 5), 32u); ssd_item(a, layer, item, lds); }
.LBB0_175:
	s_or_b64 exec, exec, s[18:19]
	v_readlane_b32 s2, v255, 41
	s_nop 3
	s_cmp_eq_u32 s2, 2
	s_cbranch_scc1 .LBB0_209
.Lp4_ssd_entry:
	s_and_b64 vcc, exec, s[28:29]
	s_cbranch_vccz .Lp4_tail
	v_readlane_b32 s2, v255, 12
	s_mulk_i32 s2, 0x7800
	s_mul_hi_u32 s3, s8, 0x7800
	s_add_i32 s28, s3, s2
	s_lshl_b32 s29, s8, 5
	s_lshl_b32 s58, s8, 4
	s_mov_b32 s59, s36
	s_branch .LBB0_178
.Lp4_tail:
	v_readlane_b32 s2, v255, 41
	s_nop 3
	s_cmp_lg_u32 s2, 1
	s_cbranch_scc1 .LBB0_209
	s_mov_b32 s2, 2
	s_nop 1
	v_writelane_b32 v255, s2, 41
	s_branch .Lp4_conv_entry
